# waves 0-3 issue all attention LDS-DMA; waves 4-7 at priority 1 for the first 16 MFMAs of every tile step
# baseline (speedup 1.0000x reference)
.Lattn_dma_a:
	v_cvt_f32_i32_e32 v98, s82
	v_add_u32_e32 v183, s79, v218
	v_add_f32_e32 v98, v155, v98
	v_fma_f32 v224, v200, v98, -v199
	v_fma_f32 v98, 0, v200, v224
	v_add_f32_e32 v99, v200, v224
	v_fma_f32 v100, v200, s64, v224
	v_fma_f32 v101, v200, s65, v224
	v_fma_f32 v102, v200, s66, v224
	v_fma_f32 v103, v200, s67, v224
	v_mul_f32_e32 v240, 0x42000000, v200
	ds_read_b128 v[228:231], v181 offset:53248
	s_waitcnt lgkmcnt(2)
	v_mfma_f32_32x32x16_bf16 v[18:33], v[126:129], v[106:109], v[18:33]
	v_add_f32_e32 v254, v70, v254
	v_add_f32_e32 v255, v252, v255
	v_exp_f32_e32 v71, v71
	v_fma_f32 v104, v200, s68, v224
	v_fma_f32 v105, v200, s69, v224
	ds_read_b128 v[126:129], v181 offset:57344
	v_mfma_f32_32x32x16_bf16 v[2:17], v[118:121], v[106:109], v[2:17]
	v_add_f32_e32 v254, v71, v254
	v_exp_f32_e32 v253, v87
	v_exp_f32_e32 v82, v72
	ds_read_b128 v[118:121], v181 offset:61440
	s_waitcnt lgkmcnt(2)
	v_mfma_f32_32x32x16_bf16 v[50:65], v[122:125], v[110:113], v[50:65]
	v_add_f32_e32 v255, v253, v255
	v_add_f32_e32 v254, v82, v254
	v_exp_f32_e32 v72, v88
	v_fma_f32 v106, v200, s70, v224
	v_fma_f32 v107, v200, s71, v224
	v_add_u32_e32 v179, v179, v226
	ds_read_b128 v[122:125], v179 offset:49152
	v_mfma_f32_32x32x16_bf16 v[34:49], v[228:231], v[110:113], v[34:49]
	v_add_f32_e32 v255, v72, v255
	v_exp_f32_e32 v83, v73
	v_exp_f32_e32 v73, v89
	ds_read_b128 v[228:231], v179 offset:53248
	s_waitcnt lgkmcnt(2)
	v_mfma_f32_32x32x16_bf16 v[18:33], v[126:129], v[110:113], v[18:33]
	v_add_f32_e32 v254, v83, v254
	v_add_f32_e32 v255, v73, v255
	v_exp_f32_e32 v74, v74
	v_fma_f32 v108, v200, s72, v224
	v_fma_f32 v109, v200, s73, v224
	ds_read_b128 v[126:129], v179 offset:57344
	v_mfma_f32_32x32x16_bf16 v[2:17], v[118:121], v[110:113], v[2:17]
	v_add_f32_e32 v254, v74, v254
	v_exp_f32_e32 v90, v90
	v_exp_f32_e32 v75, v75
	ds_read_b128 v[118:121], v179 offset:61440
	s_waitcnt lgkmcnt(2)
	v_mfma_f32_32x32x16_bf16 v[50:65], v[122:125], v[114:117], v[50:65]
	v_add_f32_e32 v255, v90, v255
	v_add_f32_e32 v254, v75, v254
	v_exp_f32_e32 v91, v91
	v_fma_f32 v110, v200, s74, v224
	v_fma_f32 v111, v200, s75, v224
	v_add_u32_e32 v112, v183, v149
	ds_read_b128 v[232:235], v112
	v_mfma_f32_32x32x16_bf16 v[34:49], v[228:231], v[114:117], v[34:49]
	v_add_f32_e32 v255, v91, v255
	v_exp_f32_e32 v76, v76
	v_exp_f32_e32 v92, v92
	ds_read_b128 v[228:231], v112 offset:4096
	s_waitcnt lgkmcnt(2)
	v_mfma_f32_32x32x16_bf16 v[18:33], v[126:129], v[114:117], v[18:33]
	v_add_f32_e32 v254, v76, v254
	v_add_f32_e32 v255, v92, v255
	v_exp_f32_e32 v77, v77
	v_fma_f32 v112, v200, s76, v224
	v_fma_f32 v113, v200, s77, v224
	v_add_u32_e32 v179, v183, v208
	ds_read_b128 v[236:239], v179
	v_mfma_f32_32x32x16_bf16 v[2:17], v[118:121], v[114:117], v[2:17]
	s_setprio 0
	v_add_f32_e64 v114, v240, v98
	v_add_f32_e64 v115, v240, v99
	v_add_f32_e64 v128, v240, v112
	v_add_f32_e64 v129, v240, v113
	v_add_f32_e64 v126, v240, v110
	v_add_f32_e64 v127, v240, v111
	v_add_f32_e32 v124, v240, v108
	v_add_f32_e32 v125, v240, v109
	v_add_f32_e32 v122, v240, v106
	v_add_f32_e32 v123, v240, v107
	v_add_f32_e32 v120, v240, v104
	v_add_f32_e32 v121, v240, v105
	v_add_f32_e32 v118, v240, v102
	v_add_f32_e32 v119, v240, v103
	v_add_f32_e32 v116, v240, v100
	v_add_f32_e32 v117, v240, v101
	ds_read_b128 v[240:243], v179 offset:4096
	s_waitcnt lgkmcnt(2)
	v_mfma_f32_32x32x16_bf16 v[98:113], v[232:235], v[130:133], v[98:113]
	v_add_f32_e32 v254, v77, v254
	v_exp_f32_e32 v93, v93
	v_exp_f32_e32 v78, v78
	v_add_u32_e32 v179, v183, v209
	ds_read_b128 v[232:235], v179
	v_mfma_f32_32x32x16_bf16 v[114:129], v[228:231], v[130:133], v[114:129]
	v_add_f32_e32 v255, v93, v255
	v_add_f32_e32 v254, v78, v254
	v_exp_f32_e32 v94, v94
	v_exp_f32_e32 v79, v79
	ds_read_b128 v[228:231], v179 offset:4096
	s_waitcnt lgkmcnt(2)
	v_mfma_f32_32x32x16_bf16 v[98:113], v[236:239], v[134:137], v[98:113]
	v_add_f32_e32 v255, v94, v255
	v_add_f32_e32 v254, v79, v254
	v_exp_f32_e32 v95, v95
	v_exp_f32_e32 v80, v80
	v_add_u32_e32 v179, v183, v226
	ds_read_b128 v[236:239], v179
	v_mfma_f32_32x32x16_bf16 v[114:129], v[240:243], v[134:137], v[114:129]
	v_add_f32_e32 v255, v95, v255
	v_add_f32_e32 v254, v80, v254
	v_exp_f32_e32 v96, v96
	v_exp_f32_e32 v81, v81
	ds_read_b128 v[240:243], v179 offset:4096
	s_waitcnt lgkmcnt(2)
	v_mfma_f32_32x32x16_bf16 v[98:113], v[232:235], v[138:141], v[98:113]
	v_add_f32_e32 v255, v96, v255
	v_add_f32_e32 v254, v81, v254
	v_exp_f32_e32 v97, v97
	v_mfma_f32_32x32x16_bf16 v[114:129], v[228:231], v[138:141], v[114:129]
	v_add_f32_e32 v255, v97, v255
	v_add_f32_e32 v254, v255, v254
	s_waitcnt lgkmcnt(0)
	v_mfma_f32_32x32x16_bf16 v[98:113], v[236:239], v[142:145], v[98:113]
	v_mfma_f32_32x32x16_bf16 v[114:129], v[240:243], v[142:145], v[114:129]
	s_cmp_lg_u32 s4, 0
	s_cbranch_scc0 .LBB0_471
	s_waitcnt vmcnt(8) lgkmcnt(0)
	s_barrier
	s_cmp_eq_u32 s100, 0
	s_cbranch_scc1 .Lattn_fair_a
	s_setprio 1

.Lattn_dma_b:
	v_cvt_f32_i32_e32 v66, s78
	v_exp_f32_e32 v231, v98
	v_add_f32_e32 v66, v155, v66
	v_fma_f32 v230, v228, v66, -v199
	v_add_u32_e32 v229, s10, v218
	v_exp_f32_e32 v233, v114
	v_fma_f32 v66, 0, v228, v230
	v_exp_f32_e32 v234, v99
	v_exp_f32_e32 v235, v115
	v_add_f32_e32 v67, v228, v230
	v_exp_f32_e32 v236, v100
	v_exp_f32_e32 v237, v116
	v_exp_f32_e32 v238, v101
	v_exp_f32_e32 v239, v117
	v_fma_f32 v68, v228, s64, v230
	v_fma_f32 v69, v228, s65, v230
	v_fma_f32 v70, v228, s66, v230
	v_fma_f32 v71, v228, s67, v230
	v_cvt_pk_bf16_f32 v98, v249, v250
	v_cvt_pk_bf16_f32 v99, v195, v251
	v_cvt_pk_bf16_f32 v100, v252, v253
	v_cvt_pk_bf16_f32 v101, v72, v73
	v_cvt_pk_bf16_f32 v114, v90, v91
	v_cvt_pk_bf16_f32 v115, v92, v93
	v_cvt_pk_bf16_f32 v116, v94, v95
	v_cvt_pk_bf16_f32 v117, v96, v97
	v_mul_f32_e32 v232, 0x42000000, v228
	v_exp_f32_e32 v240, v102
	v_exp_f32_e32 v241, v118
	v_exp_f32_e32 v242, v103
	v_exp_f32_e32 v243, v119
	ds_read_b128 v[90:93], v227 offset:53248
	s_waitcnt lgkmcnt(2)
	v_mfma_f32_32x32x16_bf16 v[18:33], v[86:89], v[74:77], v[18:33]
	v_add_f32_e32 v254, 0, v231
	v_add_f32_e32 v255, 0, v233
	v_fma_f32 v72, v228, s68, v230
	v_fma_f32 v73, v228, s69, v230
	v_exp_f32_e32 v181, v104
	v_exp_f32_e32 v183, v120
	ds_read_b128 v[86:89], v227 offset:57344
	v_mfma_f32_32x32x16_bf16 v[2:17], v[82:85], v[74:77], v[2:17]
	v_add_f32_e32 v254, v234, v254
	v_add_f32_e32 v255, v235, v255
	v_exp_f32_e32 v195, v105
	v_exp_f32_e32 v200, v121
	ds_read_b128 v[82:85], v227 offset:61440
	s_waitcnt lgkmcnt(2)
	v_mfma_f32_32x32x16_bf16 v[50:65], v[78:81], v[98:101], v[50:65]
	v_add_f32_e32 v254, v236, v254
	v_add_f32_e32 v255, v237, v255
	v_fma_f32 v74, v228, s70, v230
	v_fma_f32 v75, v228, s71, v230
	v_exp_f32_e32 v224, v106
	v_exp_f32_e32 v122, v122
	v_add_u32_e32 v78, v198, v226
	ds_read_b128 v[94:97], v78 offset:49152
	v_mfma_f32_32x32x16_bf16 v[34:49], v[90:93], v[98:101], v[34:49]
	v_add_f32_e32 v254, v238, v254
	v_add_f32_e32 v255, v239, v255
	v_exp_f32_e32 v225, v107
	v_exp_f32_e32 v123, v123
	ds_read_b128 v[90:93], v78 offset:53248
	s_waitcnt lgkmcnt(2)
	v_mfma_f32_32x32x16_bf16 v[18:33], v[86:89], v[98:101], v[18:33]
	v_add_f32_e32 v254, v240, v254
	v_add_f32_e32 v255, v241, v255
	v_fma_f32 v76, v228, s72, v230
	v_fma_f32 v77, v228, s73, v230
	v_exp_f32_e32 v227, v108
	v_exp_f32_e32 v124, v124
	ds_read_b128 v[86:89], v78 offset:57344
	v_mfma_f32_32x32x16_bf16 v[2:17], v[82:85], v[98:101], v[2:17]
	v_add_f32_e32 v254, v242, v254
	v_add_f32_e32 v255, v243, v255
	v_exp_f32_e32 v244, v109
	v_exp_f32_e32 v125, v125
	ds_read_b128 v[98:101], v78 offset:61440
	s_waitcnt lgkmcnt(2)
	v_mfma_f32_32x32x16_bf16 v[50:65], v[94:97], v[114:117], v[50:65]
	v_add_f32_e32 v254, v181, v254
	v_add_f32_e32 v255, v183, v255
	v_fma_f32 v78, v228, s74, v230
	v_fma_f32 v79, v228, s75, v230
	v_exp_f32_e32 v245, v110
	v_exp_f32_e32 v126, v126
	v_add_u32_e32 v80, v229, v149
	ds_read_b128 v[102:105], v80
	v_mfma_f32_32x32x16_bf16 v[34:49], v[90:93], v[114:117], v[34:49]
	v_add_f32_e32 v254, v195, v254
	v_add_f32_e32 v255, v200, v255
	v_exp_f32_e32 v246, v111
	v_exp_f32_e32 v127, v127
	ds_read_b128 v[106:109], v80 offset:4096
	s_waitcnt lgkmcnt(2)
	v_mfma_f32_32x32x16_bf16 v[18:33], v[86:89], v[114:117], v[18:33]
	v_add_f32_e32 v254, v224, v254
	v_add_f32_e32 v255, v122, v255
	v_fma_f32 v80, v228, s76, v230
	v_fma_f32 v81, v228, s77, v230
	v_exp_f32_e32 v247, v112
	v_exp_f32_e32 v128, v128
	v_add_u32_e32 v110, v229, v208
	ds_read_b128 v[118:121], v110
	v_mfma_f32_32x32x16_bf16 v[2:17], v[98:101], v[114:117], v[2:17]
	s_setprio 0
	v_add_f32_e32 v254, v225, v254
	v_add_f32_e32 v255, v123, v255
	v_add_f32_e64 v82, v232, v66
	v_add_f32_e64 v83, v232, v67
	v_add_f32_e64 v96, v232, v80
	v_add_f32_e64 v97, v232, v81
	v_add_f32_e64 v94, v232, v78
	v_add_f32_e64 v95, v232, v79
	v_add_f32_e32 v92, v232, v76
	v_add_f32_e32 v93, v232, v77
	v_add_f32_e32 v90, v232, v74
	v_add_f32_e32 v91, v232, v75
	v_add_f32_e32 v88, v232, v72
	v_add_f32_e32 v89, v232, v73
	v_add_f32_e32 v86, v232, v70
	v_add_f32_e32 v87, v232, v71
	v_add_f32_e32 v84, v232, v68
	v_add_f32_e32 v85, v232, v69
	v_exp_f32_e32 v228, v113
	v_exp_f32_e32 v129, v129
	ds_read_b128 v[98:101], v110 offset:4096
	s_waitcnt lgkmcnt(2)
	v_mfma_f32_32x32x16_bf16 v[66:81], v[102:105], v[130:133], v[66:81]
	v_add_f32_e32 v254, v227, v254
	v_add_f32_e32 v255, v124, v255
	v_add_f32_e32 v254, v244, v254
	v_add_u32_e32 v110, v229, v209
	ds_read_b128 v[102:105], v110
	v_mfma_f32_32x32x16_bf16 v[82:97], v[106:109], v[130:133], v[82:97]
	v_add_f32_e32 v255, v125, v255
	v_add_f32_e32 v254, v245, v254
	v_add_f32_e32 v255, v126, v255
	ds_read_b128 v[106:109], v110 offset:4096
	s_waitcnt lgkmcnt(2)
	v_mfma_f32_32x32x16_bf16 v[66:81], v[118:121], v[134:137], v[66:81]
	v_add_f32_e32 v254, v246, v254
	v_add_f32_e32 v255, v127, v255
	v_add_f32_e32 v254, v247, v254
	v_add_u32_e32 v114, v229, v226
	ds_read_b128 v[110:113], v114
	v_mfma_f32_32x32x16_bf16 v[82:97], v[98:101], v[134:137], v[82:97]
	v_add_f32_e32 v255, v128, v255
	v_add_f32_e32 v254, v228, v254
	v_add_f32_e32 v255, v129, v255
	v_add_f32_e32 v254, v255, v254
	ds_read_b128 v[98:101], v114 offset:4096
	s_waitcnt lgkmcnt(2)
	v_mfma_f32_32x32x16_bf16 v[66:81], v[102:105], v[138:141], v[66:81]
	v_cvt_pk_bf16_f32 v114, v122, v123
	v_cvt_pk_bf16_f32 v115, v124, v125
	v_cvt_pk_bf16_f32 v116, v126, v127
	v_cvt_pk_bf16_f32 v117, v128, v129
	v_mfma_f32_32x32x16_bf16 v[82:97], v[106:109], v[138:141], v[82:97]
	v_cvt_pk_bf16_f32 v106, v224, v225
	v_cvt_pk_bf16_f32 v107, v227, v244
	v_cvt_pk_bf16_f32 v108, v245, v246
	v_cvt_pk_bf16_f32 v109, v247, v228
	s_waitcnt lgkmcnt(0)
	v_mfma_f32_32x32x16_bf16 v[66:81], v[110:113], v[142:145], v[66:81]
	v_cvt_pk_bf16_f32 v110, v233, v235
	v_cvt_pk_bf16_f32 v111, v237, v239
	v_cvt_pk_bf16_f32 v112, v241, v243
	v_cvt_pk_bf16_f32 v113, v183, v200
	v_mfma_f32_32x32x16_bf16 v[82:97], v[98:101], v[142:145], v[82:97]
	s_add_i32 s10, s4, 1
	s_cmp_lg_u32 s4, 2
	s_cselect_b32 s62, s10, 0
	s_add_i32 s4, s5, 1
	s_cmp_lg_u32 s5, 2
	s_cselect_b32 s10, s4, 0
	s_add_i32 s34, s34, 2
	v_add_f32_e32 v198, v179, v254
	v_cvt_pk_bf16_f32 v98, v231, v234
	v_cvt_pk_bf16_f32 v99, v236, v238
	v_cvt_pk_bf16_f32 v100, v240, v242
	v_cvt_pk_bf16_f32 v101, v181, v195
	s_cmp_ge_i32 s61, s48
	s_cbranch_scc1 .LBB0_473
	s_mov_b32 s60, s63
	s_add_i32 s61, s34, -2
	s_cmp_gt_i32 s61, s48
	s_cbranch_scc1 .LBB0_469
